# leading half starts its SwiGLU epilogue (first row group) before the un-stagger barrier, overlapping the other half's last MFMA segment
# baseline (speedup 1.0000x reference)
.Lg131_mid:
	ds_read_b128 v[152:155], v164
	ds_read_b128 v[156:159], v164 offset:1024
	ds_read_b128 v[160:163], v164 offset:2048
	ds_read_b128 v[164:167], v164 offset:3072
	s_add_u32 s28, s28, 0x40000
	s_addc_u32 s29, s29, 0
	s_mov_b32 m0, s43
	ds_read_b128 v[168:171], v150 offset:32768
	ds_read_b128 v[172:175], v150 offset:33792
	ds_read_b128 v[176:179], v150 offset:34816
	ds_read_b128 v[180:183], v150 offset:35840
	ds_read_b128 v[184:187], v150 offset:36864
	ds_read_b128 v[188:191], v150 offset:37888
	ds_read_b128 v[192:195], v150 offset:38912
	ds_read_b128 v[196:199], v150 offset:39936
	global_load_lds_dwordx4 v134, s[28:29]
	s_mov_b32 m0, s44
	s_nop 0
	global_load_lds_dwordx4 v130, s[28:29]
	s_waitcnt lgkmcnt(8)
	s_barrier
	s_waitcnt lgkmcnt(0)
	s_waitcnt lgkmcnt(0)
	v_mfma_f32_16x16x32_bf16 v[124:127], v[152:155], v[168:171], v[124:127]
	v_mfma_f32_16x16x32_bf16 v[120:123], v[160:163], v[168:171], v[120:123]
	v_mfma_f32_16x16x32_bf16 v[108:111], v[152:155], v[176:179], v[108:111]
	v_mfma_f32_16x16x32_bf16 v[104:107], v[160:163], v[176:179], v[104:107]
	v_mfma_f32_16x16x32_bf16 v[92:95], v[152:155], v[184:187], v[92:95]
	v_mfma_f32_16x16x32_bf16 v[88:91], v[160:163], v[184:187], v[88:91]
	v_mfma_f32_16x16x32_bf16 v[76:79], v[152:155], v[192:195], v[76:79]
	v_mfma_f32_16x16x32_bf16 v[72:75], v[160:163], v[192:195], v[72:75]
	v_mfma_f32_16x16x32_bf16 v[124:127], v[156:159], v[172:175], v[124:127]
	v_mfma_f32_16x16x32_bf16 v[120:123], v[164:167], v[172:175], v[120:123]
	v_mfma_f32_16x16x32_bf16 v[108:111], v[156:159], v[180:183], v[108:111]
	v_mfma_f32_16x16x32_bf16 v[104:107], v[164:167], v[180:183], v[104:107]
	v_mfma_f32_16x16x32_bf16 v[92:95], v[156:159], v[188:191], v[92:95]
	v_mfma_f32_16x16x32_bf16 v[88:91], v[164:167], v[188:191], v[88:91]
	v_mfma_f32_16x16x32_bf16 v[76:79], v[156:159], v[196:199], v[76:79]
	v_mfma_f32_16x16x32_bf16 v[72:75], v[164:167], v[196:199], v[72:75]
	s_barrier
	s_add_i32 s28, 0, 0x1c000
	s_add_i32 s29, s58, s38
	v_add_u32_e32 v212, s28, v145
	s_mov_b32 m0, s29
	ds_read_b128 v[200:203], v212
	ds_read_b128 v[204:207], v212 offset:1024
	ds_read_b128 v[208:211], v212 offset:2048
	ds_read_b128 v[212:215], v212 offset:3072
	global_load_lds_dwordx4 v132, s[80:81]
	s_add_i32 m0, s29, 0x2000
	s_nop 0
	global_load_lds_dwordx4 v128, s[80:81]
	s_waitcnt vmcnt(10)
	s_barrier
	s_waitcnt lgkmcnt(0)
	s_waitcnt lgkmcnt(0)
	v_mfma_f32_16x16x32_bf16 v[116:119], v[200:203], v[168:171], v[116:119]
	v_mfma_f32_16x16x32_bf16 v[112:115], v[208:211], v[168:171], v[112:115]
	v_mfma_f32_16x16x32_bf16 v[100:103], v[200:203], v[176:179], v[100:103]
	v_mfma_f32_16x16x32_bf16 v[96:99], v[208:211], v[176:179], v[96:99]
	v_mfma_f32_16x16x32_bf16 v[84:87], v[200:203], v[184:187], v[84:87]
	v_mfma_f32_16x16x32_bf16 v[80:83], v[208:211], v[184:187], v[80:83]
	v_mfma_f32_16x16x32_bf16 v[68:71], v[200:203], v[192:195], v[68:71]
	v_mfma_f32_16x16x32_bf16 v[64:67], v[208:211], v[192:195], v[64:67]
	v_mfma_f32_16x16x32_bf16 v[116:119], v[204:207], v[172:175], v[116:119]
	v_mfma_f32_16x16x32_bf16 v[112:115], v[212:215], v[172:175], v[112:115]
	v_mfma_f32_16x16x32_bf16 v[100:103], v[204:207], v[180:183], v[100:103]
	v_mfma_f32_16x16x32_bf16 v[96:99], v[212:215], v[180:183], v[96:99]
	v_mfma_f32_16x16x32_bf16 v[84:87], v[204:207], v[188:191], v[84:87]
	v_mfma_f32_16x16x32_bf16 v[80:83], v[212:215], v[188:191], v[80:83]
	v_mfma_f32_16x16x32_bf16 v[68:71], v[204:207], v[196:199], v[68:71]
	v_mfma_f32_16x16x32_bf16 v[64:67], v[212:215], v[196:199], v[64:67]
	s_mov_b32 m0, s45
	s_barrier
	ds_read_b128 v[168:171], v150 offset:49152
	ds_read_b128 v[172:175], v150 offset:50176
	ds_read_b128 v[176:179], v150 offset:51200
	ds_read_b128 v[180:183], v150 offset:52224
	ds_read_b128 v[184:187], v150 offset:53248
	ds_read_b128 v[188:191], v150 offset:54272
	ds_read_b128 v[192:195], v150 offset:55296
	ds_read_b128 v[196:199], v150 offset:56320
	global_load_lds_dwordx4 v134, s[82:83]
	s_mov_b32 m0, s46
	s_nop 0
	global_load_lds_dwordx4 v130, s[82:83]
	s_barrier
	s_waitcnt lgkmcnt(0)
	s_waitcnt lgkmcnt(0)
	v_mfma_f32_16x16x32_bf16 v[60:63], v[152:155], v[168:171], v[60:63]
	v_mfma_f32_16x16x32_bf16 v[56:59], v[160:163], v[168:171], v[56:59]
	v_mfma_f32_16x16x32_bf16 v[44:47], v[152:155], v[176:179], v[44:47]
	v_mfma_f32_16x16x32_bf16 v[40:43], v[160:163], v[176:179], v[40:43]
	v_mfma_f32_16x16x32_bf16 v[28:31], v[152:155], v[184:187], v[28:31]
	v_mfma_f32_16x16x32_bf16 v[24:27], v[160:163], v[184:187], v[24:27]
	v_mfma_f32_16x16x32_bf16 v[12:15], v[152:155], v[192:195], v[12:15]
	v_mfma_f32_16x16x32_bf16 v[8:11], v[160:163], v[192:195], v[8:11]
	v_mfma_f32_16x16x32_bf16 v[60:63], v[156:159], v[172:175], v[60:63]
	v_mfma_f32_16x16x32_bf16 v[56:59], v[164:167], v[172:175], v[56:59]
	v_mfma_f32_16x16x32_bf16 v[44:47], v[156:159], v[180:183], v[44:47]
	v_mfma_f32_16x16x32_bf16 v[40:43], v[164:167], v[180:183], v[40:43]
	v_mfma_f32_16x16x32_bf16 v[28:31], v[156:159], v[188:191], v[28:31]
	v_mfma_f32_16x16x32_bf16 v[24:27], v[164:167], v[188:191], v[24:27]
	v_mfma_f32_16x16x32_bf16 v[12:15], v[156:159], v[196:199], v[12:15]
	v_mfma_f32_16x16x32_bf16 v[8:11], v[164:167], v[196:199], v[8:11]
	s_barrier
	s_add_u32 s26, s26, 0x40080
	s_addc_u32 s27, s27, 0
	s_add_i32 s28, s28, s38
	s_mov_b32 m0, s28
	s_nop 0
	global_load_lds_dwordx4 v132, s[26:27]
	s_add_i32 m0, s28, 0x2000
	s_nop 0
	global_load_lds_dwordx4 v128, s[26:27]
	s_waitcnt vmcnt(8)
	s_barrier
	v_mfma_f32_16x16x32_bf16 v[52:55], v[200:203], v[168:171], v[52:55]
	v_mfma_f32_16x16x32_bf16 v[48:51], v[208:211], v[168:171], v[48:51]
	v_mfma_f32_16x16x32_bf16 v[36:39], v[200:203], v[176:179], v[36:39]
	v_mfma_f32_16x16x32_bf16 v[32:35], v[208:211], v[176:179], v[32:35]
	v_mfma_f32_16x16x32_bf16 v[20:23], v[200:203], v[184:187], v[20:23]
	v_mfma_f32_16x16x32_bf16 v[16:19], v[208:211], v[184:187], v[16:19]
	v_mfma_f32_16x16x32_bf16 v[4:7], v[200:203], v[192:195], v[4:7]
	v_mfma_f32_16x16x32_bf16 v[0:3], v[208:211], v[192:195], v[0:3]
	v_mfma_f32_16x16x32_bf16 v[52:55], v[204:207], v[172:175], v[52:55]
	v_mfma_f32_16x16x32_bf16 v[48:51], v[212:215], v[172:175], v[48:51]
	v_mfma_f32_16x16x32_bf16 v[36:39], v[204:207], v[180:183], v[36:39]
	v_mfma_f32_16x16x32_bf16 v[32:35], v[212:215], v[180:183], v[32:35]
	v_mfma_f32_16x16x32_bf16 v[20:23], v[204:207], v[188:191], v[20:23]
	v_mfma_f32_16x16x32_bf16 v[16:19], v[212:215], v[188:191], v[16:19]
	v_mfma_f32_16x16x32_bf16 v[4:7], v[204:207], v[196:199], v[4:7]
	v_mfma_f32_16x16x32_bf16 v[0:3], v[212:215], v[196:199], v[0:3]
	s_add_i32 s57, s57, 2
	s_add_u32 s20, s20, 0x100
	s_addc_u32 s21, s21, 0
	s_add_u32 s55, s55, 0x100
	s_addc_u32 s56, s56, 0
	s_cmp_gt_u32 s57, 13
	s_barrier
	s_cbranch_scc0 .LBB0_131
	s_setprio 0
	v_lshl_add_u32 v180, s51, 10, v147
	ds_read2_b32 v[152:153], v180 offset1:16
	ds_read2_b32 v[154:155], v180 offset0:32 offset1:48
	ds_read2_b32 v[156:157], v180 offset0:128 offset1:144
	ds_read2_b32 v[158:159], v180 offset0:160 offset1:176
	v_lshl_or_b32 v181, s52, 7, v148
	v_lshl_add_u32 v182, s18, 8, v144
	s_and_b64 vcc, exec, s[4:5]
	s_mov_b32 s52, s10
	s_mov_b32 s18, s12
	s_mov_b64 s[26:27], s[16:17]
	s_mov_b32 s51, s50
	s_mov_b64 s[20:21], s[14:15]
	v_mul_u32_u24_e32 v183, s49, v182
	v_lshl_add_u32 v183, v181, 1, v183
	s_waitcnt lgkmcnt(0)
	v_mul_f32_e32 v176, 0xbfb8aa3b, v152
	v_mul_f32_e32 v177, v152, v152
	v_rcp_f32_e32 v178, v177
	v_pk_mul_f32 v[160:161], v[124:125], v[176:177] op_sel_hi:[1,0]
	v_pk_mul_f32 v[162:163], v[126:127], v[176:177] op_sel_hi:[1,0]
	v_pk_mul_f32 v[164:165], v[120:121], v[176:177] op_sel_hi:[1,0]
	v_pk_mul_f32 v[166:167], v[122:123], v[176:177] op_sel_hi:[1,0]
	v_exp_f32_e32 v160, v160
	v_exp_f32_e32 v161, v161
	v_exp_f32_e32 v162, v162
	v_exp_f32_e32 v163, v163
	v_exp_f32_e32 v164, v164
	v_exp_f32_e32 v165, v165
	v_exp_f32_e32 v166, v166
	v_exp_f32_e32 v167, v167
	v_pk_fma_f32 v[160:161], v[160:161], v[178:179], v[178:179] op_sel_hi:[1,0,0]
	v_pk_fma_f32 v[162:163], v[162:163], v[178:179], v[178:179] op_sel_hi:[1,0,0]
	v_pk_fma_f32 v[164:165], v[164:165], v[178:179], v[178:179] op_sel_hi:[1,0,0]
	v_pk_fma_f32 v[166:167], v[166:167], v[178:179], v[178:179] op_sel_hi:[1,0,0]
	v_rcp_f32_e32 v160, v160
	v_rcp_f32_e32 v161, v161
	v_rcp_f32_e32 v162, v162
	v_rcp_f32_e32 v163, v163
	v_rcp_f32_e32 v164, v164
	v_rcp_f32_e32 v165, v165
	v_rcp_f32_e32 v166, v166
	v_rcp_f32_e32 v167, v167
	v_pk_mul_f32 v[124:125], v[124:125], v[116:117]
	v_pk_mul_f32 v[126:127], v[126:127], v[118:119]
	v_pk_mul_f32 v[120:121], v[120:121], v[112:113]
	v_pk_mul_f32 v[122:123], v[122:123], v[114:115]
	v_pk_mul_f32 v[124:125], v[124:125], v[160:161]
	v_pk_mul_f32 v[126:127], v[126:127], v[162:163]
	v_pk_mul_f32 v[120:121], v[120:121], v[164:165]
	v_pk_mul_f32 v[122:123], v[122:123], v[166:167]
	v_cvt_pk_bf16_f32 v168, v124, v125
	v_cvt_pk_bf16_f32 v169, v126, v127
	v_cvt_pk_bf16_f32 v170, v120, v121
	v_cvt_pk_bf16_f32 v171, v122, v123
	global_store_dwordx4 v183, v[168:171], s[6:7]
	s_cmpk_gt_u32 s37, 0xff
	s_cbranch_scc1 .Lg131_nox
	s_barrier
	s_setprio 1
.Lg131_nox:
	v_mul_f32_e32 v176, 0xbfb8aa3b, v153
	v_mul_f32_e32 v177, v153, v153
	v_rcp_f32_e32 v178, v177
	v_pk_mul_f32 v[160:161], v[108:109], v[176:177] op_sel_hi:[1,0]
	v_pk_mul_f32 v[162:163], v[110:111], v[176:177] op_sel_hi:[1,0]
	v_pk_mul_f32 v[164:165], v[104:105], v[176:177] op_sel_hi:[1,0]
	v_pk_mul_f32 v[166:167], v[106:107], v[176:177] op_sel_hi:[1,0]
	v_exp_f32_e32 v160, v160
	v_exp_f32_e32 v161, v161
	v_exp_f32_e32 v162, v162
	v_exp_f32_e32 v163, v163
	v_exp_f32_e32 v164, v164
	v_exp_f32_e32 v165, v165
	v_exp_f32_e32 v166, v166
	v_exp_f32_e32 v167, v167
	v_pk_fma_f32 v[160:161], v[160:161], v[178:179], v[178:179] op_sel_hi:[1,0,0]
	v_pk_fma_f32 v[162:163], v[162:163], v[178:179], v[178:179] op_sel_hi:[1,0,0]
	v_pk_fma_f32 v[164:165], v[164:165], v[178:179], v[178:179] op_sel_hi:[1,0,0]
	v_pk_fma_f32 v[166:167], v[166:167], v[178:179], v[178:179] op_sel_hi:[1,0,0]
	v_rcp_f32_e32 v160, v160
	v_rcp_f32_e32 v161, v161
	v_rcp_f32_e32 v162, v162
	v_rcp_f32_e32 v163, v163
	v_rcp_f32_e32 v164, v164
	v_rcp_f32_e32 v165, v165
	v_rcp_f32_e32 v166, v166
	v_rcp_f32_e32 v167, v167
	v_pk_mul_f32 v[108:109], v[108:109], v[100:101]
	v_pk_mul_f32 v[110:111], v[110:111], v[102:103]
	v_pk_mul_f32 v[104:105], v[104:105], v[96:97]
	v_pk_mul_f32 v[106:107], v[106:107], v[98:99]
	v_pk_mul_f32 v[108:109], v[108:109], v[160:161]
	v_pk_mul_f32 v[110:111], v[110:111], v[162:163]
	v_pk_mul_f32 v[104:105], v[104:105], v[164:165]
	v_pk_mul_f32 v[106:107], v[106:107], v[166:167]
	v_cvt_pk_bf16_f32 v172, v108, v109
	v_cvt_pk_bf16_f32 v173, v110, v111
	v_cvt_pk_bf16_f32 v174, v104, v105
	v_cvt_pk_bf16_f32 v175, v106, v107
	v_add_u32_e32 v185, 0x16000, v183
	global_store_dwordx4 v185, v[172:175], s[6:7]
	v_mul_f32_e32 v176, 0xbfb8aa3b, v154
	v_mul_f32_e32 v177, v154, v154
	v_rcp_f32_e32 v178, v177
	v_pk_mul_f32 v[160:161], v[92:93], v[176:177] op_sel_hi:[1,0]
	v_pk_mul_f32 v[162:163], v[94:95], v[176:177] op_sel_hi:[1,0]
	v_pk_mul_f32 v[164:165], v[88:89], v[176:177] op_sel_hi:[1,0]
	v_pk_mul_f32 v[166:167], v[90:91], v[176:177] op_sel_hi:[1,0]
	v_exp_f32_e32 v160, v160
	v_exp_f32_e32 v161, v161
	v_exp_f32_e32 v162, v162
	v_exp_f32_e32 v163, v163
	v_exp_f32_e32 v164, v164
	v_exp_f32_e32 v165, v165
	v_exp_f32_e32 v166, v166
	v_exp_f32_e32 v167, v167
	v_pk_fma_f32 v[160:161], v[160:161], v[178:179], v[178:179] op_sel_hi:[1,0,0]
	v_pk_fma_f32 v[162:163], v[162:163], v[178:179], v[178:179] op_sel_hi:[1,0,0]
	v_pk_fma_f32 v[164:165], v[164:165], v[178:179], v[178:179] op_sel_hi:[1,0,0]
	v_pk_fma_f32 v[166:167], v[166:167], v[178:179], v[178:179] op_sel_hi:[1,0,0]
	v_rcp_f32_e32 v160, v160
	v_rcp_f32_e32 v161, v161
	v_rcp_f32_e32 v162, v162
	v_rcp_f32_e32 v163, v163
	v_rcp_f32_e32 v164, v164
	v_rcp_f32_e32 v165, v165
	v_rcp_f32_e32 v166, v166
	v_rcp_f32_e32 v167, v167
	v_pk_mul_f32 v[92:93], v[92:93], v[84:85]
	v_pk_mul_f32 v[94:95], v[94:95], v[86:87]
	v_pk_mul_f32 v[88:89], v[88:89], v[80:81]
	v_pk_mul_f32 v[90:91], v[90:91], v[82:83]
	v_pk_mul_f32 v[92:93], v[92:93], v[160:161]
	v_pk_mul_f32 v[94:95], v[94:95], v[162:163]
	v_pk_mul_f32 v[88:89], v[88:89], v[164:165]
	v_pk_mul_f32 v[90:91], v[90:91], v[166:167]
	v_cvt_pk_bf16_f32 v168, v92, v93
	v_cvt_pk_bf16_f32 v169, v94, v95
	v_cvt_pk_bf16_f32 v170, v88, v89
	v_cvt_pk_bf16_f32 v171, v90, v91
	v_add_u32_e32 v184, 0x2c000, v183
	global_store_dwordx4 v184, v[168:171], s[6:7]
	v_mul_f32_e32 v176, 0xbfb8aa3b, v155
	v_mul_f32_e32 v177, v155, v155
	v_rcp_f32_e32 v178, v177
	v_pk_mul_f32 v[160:161], v[76:77], v[176:177] op_sel_hi:[1,0]
	v_pk_mul_f32 v[162:163], v[78:79], v[176:177] op_sel_hi:[1,0]
	v_pk_mul_f32 v[164:165], v[72:73], v[176:177] op_sel_hi:[1,0]
	v_pk_mul_f32 v[166:167], v[74:75], v[176:177] op_sel_hi:[1,0]
	v_exp_f32_e32 v160, v160
	v_exp_f32_e32 v161, v161
	v_exp_f32_e32 v162, v162
	v_exp_f32_e32 v163, v163
	v_exp_f32_e32 v164, v164
	v_exp_f32_e32 v165, v165
	v_exp_f32_e32 v166, v166
	v_exp_f32_e32 v167, v167
	v_pk_fma_f32 v[160:161], v[160:161], v[178:179], v[178:179] op_sel_hi:[1,0,0]
	v_pk_fma_f32 v[162:163], v[162:163], v[178:179], v[178:179] op_sel_hi:[1,0,0]
	v_pk_fma_f32 v[164:165], v[164:165], v[178:179], v[178:179] op_sel_hi:[1,0,0]
	v_pk_fma_f32 v[166:167], v[166:167], v[178:179], v[178:179] op_sel_hi:[1,0,0]
	v_rcp_f32_e32 v160, v160
	v_rcp_f32_e32 v161, v161
	v_rcp_f32_e32 v162, v162
	v_rcp_f32_e32 v163, v163
	v_rcp_f32_e32 v164, v164
	v_rcp_f32_e32 v165, v165
	v_rcp_f32_e32 v166, v166
	v_rcp_f32_e32 v167, v167
	v_pk_mul_f32 v[76:77], v[76:77], v[68:69]
	v_pk_mul_f32 v[78:79], v[78:79], v[70:71]
	v_pk_mul_f32 v[72:73], v[72:73], v[64:65]
	v_pk_mul_f32 v[74:75], v[74:75], v[66:67]
	v_pk_mul_f32 v[76:77], v[76:77], v[160:161]
	v_pk_mul_f32 v[78:79], v[78:79], v[162:163]
	v_pk_mul_f32 v[72:73], v[72:73], v[164:165]
	v_pk_mul_f32 v[74:75], v[74:75], v[166:167]
	v_cvt_pk_bf16_f32 v172, v76, v77
	v_cvt_pk_bf16_f32 v173, v78, v79
	v_cvt_pk_bf16_f32 v174, v72, v73
	v_cvt_pk_bf16_f32 v175, v74, v75
	v_add_u32_e32 v185, 0x42000, v183
	global_store_dwordx4 v185, v[172:175], s[6:7]
	v_mul_f32_e32 v176, 0xbfb8aa3b, v156
	v_mul_f32_e32 v177, v156, v156
	v_rcp_f32_e32 v178, v177
	v_pk_mul_f32 v[160:161], v[60:61], v[176:177] op_sel_hi:[1,0]
	v_pk_mul_f32 v[162:163], v[62:63], v[176:177] op_sel_hi:[1,0]
	v_pk_mul_f32 v[164:165], v[56:57], v[176:177] op_sel_hi:[1,0]
	v_pk_mul_f32 v[166:167], v[58:59], v[176:177] op_sel_hi:[1,0]
	v_exp_f32_e32 v160, v160
	v_exp_f32_e32 v161, v161
	v_exp_f32_e32 v162, v162
	v_exp_f32_e32 v163, v163
	v_exp_f32_e32 v164, v164
	v_exp_f32_e32 v165, v165
	v_exp_f32_e32 v166, v166
	v_exp_f32_e32 v167, v167
	v_pk_fma_f32 v[160:161], v[160:161], v[178:179], v[178:179] op_sel_hi:[1,0,0]
	v_pk_fma_f32 v[162:163], v[162:163], v[178:179], v[178:179] op_sel_hi:[1,0,0]
	v_pk_fma_f32 v[164:165], v[164:165], v[178:179], v[178:179] op_sel_hi:[1,0,0]
	v_pk_fma_f32 v[166:167], v[166:167], v[178:179], v[178:179] op_sel_hi:[1,0,0]
	v_rcp_f32_e32 v160, v160
	v_rcp_f32_e32 v161, v161
	v_rcp_f32_e32 v162, v162
	v_rcp_f32_e32 v163, v163
	v_rcp_f32_e32 v164, v164
	v_rcp_f32_e32 v165, v165
	v_rcp_f32_e32 v166, v166
	v_rcp_f32_e32 v167, v167
	v_pk_mul_f32 v[60:61], v[60:61], v[52:53]
	v_pk_mul_f32 v[62:63], v[62:63], v[54:55]
	v_pk_mul_f32 v[56:57], v[56:57], v[48:49]
	v_pk_mul_f32 v[58:59], v[58:59], v[50:51]
	v_pk_mul_f32 v[60:61], v[60:61], v[160:161]
	v_pk_mul_f32 v[62:63], v[62:63], v[162:163]
	v_pk_mul_f32 v[56:57], v[56:57], v[164:165]
	v_pk_mul_f32 v[58:59], v[58:59], v[166:167]
	v_cvt_pk_bf16_f32 v168, v60, v61
	v_cvt_pk_bf16_f32 v169, v62, v63
	v_cvt_pk_bf16_f32 v170, v56, v57
	v_cvt_pk_bf16_f32 v171, v58, v59
	v_add_u32_e32 v184, 0xb0000, v183
	global_store_dwordx4 v184, v[168:171], s[6:7]
	v_mul_f32_e32 v176, 0xbfb8aa3b, v157
	v_mul_f32_e32 v177, v157, v157
	v_rcp_f32_e32 v178, v177
	v_pk_mul_f32 v[160:161], v[44:45], v[176:177] op_sel_hi:[1,0]
	v_pk_mul_f32 v[162:163], v[46:47], v[176:177] op_sel_hi:[1,0]
	v_pk_mul_f32 v[164:165], v[40:41], v[176:177] op_sel_hi:[1,0]
	v_pk_mul_f32 v[166:167], v[42:43], v[176:177] op_sel_hi:[1,0]
	v_exp_f32_e32 v160, v160
	v_exp_f32_e32 v161, v161
	v_exp_f32_e32 v162, v162
	v_exp_f32_e32 v163, v163
	v_exp_f32_e32 v164, v164
	v_exp_f32_e32 v165, v165
	v_exp_f32_e32 v166, v166
	v_exp_f32_e32 v167, v167
	v_pk_fma_f32 v[160:161], v[160:161], v[178:179], v[178:179] op_sel_hi:[1,0,0]
	v_pk_fma_f32 v[162:163], v[162:163], v[178:179], v[178:179] op_sel_hi:[1,0,0]
	v_pk_fma_f32 v[164:165], v[164:165], v[178:179], v[178:179] op_sel_hi:[1,0,0]
	v_pk_fma_f32 v[166:167], v[166:167], v[178:179], v[178:179] op_sel_hi:[1,0,0]
	v_rcp_f32_e32 v160, v160
	v_rcp_f32_e32 v161, v161
	v_rcp_f32_e32 v162, v162
	v_rcp_f32_e32 v163, v163
	v_rcp_f32_e32 v164, v164
	v_rcp_f32_e32 v165, v165
	v_rcp_f32_e32 v166, v166
	v_rcp_f32_e32 v167, v167
	v_pk_mul_f32 v[44:45], v[44:45], v[36:37]
	v_pk_mul_f32 v[46:47], v[46:47], v[38:39]
	v_pk_mul_f32 v[40:41], v[40:41], v[32:33]
	v_pk_mul_f32 v[42:43], v[42:43], v[34:35]
	v_pk_mul_f32 v[44:45], v[44:45], v[160:161]
	v_pk_mul_f32 v[46:47], v[46:47], v[162:163]
	v_pk_mul_f32 v[40:41], v[40:41], v[164:165]
	v_pk_mul_f32 v[42:43], v[42:43], v[166:167]
	v_cvt_pk_bf16_f32 v172, v44, v45
	v_cvt_pk_bf16_f32 v173, v46, v47
	v_cvt_pk_bf16_f32 v174, v40, v41
	v_cvt_pk_bf16_f32 v175, v42, v43
	v_add_u32_e32 v185, 0xc6000, v183
	global_store_dwordx4 v185, v[172:175], s[6:7]
	v_mul_f32_e32 v176, 0xbfb8aa3b, v158
	v_mul_f32_e32 v177, v158, v158
	v_rcp_f32_e32 v178, v177
	v_pk_mul_f32 v[160:161], v[28:29], v[176:177] op_sel_hi:[1,0]
	v_pk_mul_f32 v[162:163], v[30:31], v[176:177] op_sel_hi:[1,0]
	v_pk_mul_f32 v[164:165], v[24:25], v[176:177] op_sel_hi:[1,0]
	v_pk_mul_f32 v[166:167], v[26:27], v[176:177] op_sel_hi:[1,0]
	v_exp_f32_e32 v160, v160
	v_exp_f32_e32 v161, v161
	v_exp_f32_e32 v162, v162
	v_exp_f32_e32 v163, v163
	v_exp_f32_e32 v164, v164
	v_exp_f32_e32 v165, v165
	v_exp_f32_e32 v166, v166
	v_exp_f32_e32 v167, v167
	v_pk_fma_f32 v[160:161], v[160:161], v[178:179], v[178:179] op_sel_hi:[1,0,0]
	v_pk_fma_f32 v[162:163], v[162:163], v[178:179], v[178:179] op_sel_hi:[1,0,0]
	v_pk_fma_f32 v[164:165], v[164:165], v[178:179], v[178:179] op_sel_hi:[1,0,0]
	v_pk_fma_f32 v[166:167], v[166:167], v[178:179], v[178:179] op_sel_hi:[1,0,0]
	v_rcp_f32_e32 v160, v160
	v_rcp_f32_e32 v161, v161
	v_rcp_f32_e32 v162, v162
	v_rcp_f32_e32 v163, v163
	v_rcp_f32_e32 v164, v164
	v_rcp_f32_e32 v165, v165
	v_rcp_f32_e32 v166, v166
	v_rcp_f32_e32 v167, v167
	v_pk_mul_f32 v[28:29], v[28:29], v[20:21]
	v_pk_mul_f32 v[30:31], v[30:31], v[22:23]
	v_pk_mul_f32 v[24:25], v[24:25], v[16:17]
	v_pk_mul_f32 v[26:27], v[26:27], v[18:19]
	v_pk_mul_f32 v[28:29], v[28:29], v[160:161]
	v_pk_mul_f32 v[30:31], v[30:31], v[162:163]
	v_pk_mul_f32 v[24:25], v[24:25], v[164:165]
	v_pk_mul_f32 v[26:27], v[26:27], v[166:167]
	v_cvt_pk_bf16_f32 v168, v28, v29
	v_cvt_pk_bf16_f32 v169, v30, v31
	v_cvt_pk_bf16_f32 v170, v24, v25
	v_cvt_pk_bf16_f32 v171, v26, v27
	v_add_u32_e32 v184, 0xdc000, v183
	global_store_dwordx4 v184, v[168:171], s[6:7]
	v_mul_f32_e32 v176, 0xbfb8aa3b, v159
	v_mul_f32_e32 v177, v159, v159
	v_rcp_f32_e32 v178, v177
	v_pk_mul_f32 v[160:161], v[12:13], v[176:177] op_sel_hi:[1,0]
	v_pk_mul_f32 v[162:163], v[14:15], v[176:177] op_sel_hi:[1,0]
	v_pk_mul_f32 v[164:165], v[8:9], v[176:177] op_sel_hi:[1,0]
	v_pk_mul_f32 v[166:167], v[10:11], v[176:177] op_sel_hi:[1,0]
	v_exp_f32_e32 v160, v160
	v_exp_f32_e32 v161, v161
	v_exp_f32_e32 v162, v162
	v_exp_f32_e32 v163, v163
	v_exp_f32_e32 v164, v164
	v_exp_f32_e32 v165, v165
	v_exp_f32_e32 v166, v166
	v_exp_f32_e32 v167, v167
	v_pk_fma_f32 v[160:161], v[160:161], v[178:179], v[178:179] op_sel_hi:[1,0,0]
	v_pk_fma_f32 v[162:163], v[162:163], v[178:179], v[178:179] op_sel_hi:[1,0,0]
	v_pk_fma_f32 v[164:165], v[164:165], v[178:179], v[178:179] op_sel_hi:[1,0,0]
	v_pk_fma_f32 v[166:167], v[166:167], v[178:179], v[178:179] op_sel_hi:[1,0,0]
	v_rcp_f32_e32 v160, v160
	v_rcp_f32_e32 v161, v161
	v_rcp_f32_e32 v162, v162
	v_rcp_f32_e32 v163, v163
	v_rcp_f32_e32 v164, v164
	v_rcp_f32_e32 v165, v165
	v_rcp_f32_e32 v166, v166
	v_rcp_f32_e32 v167, v167
	v_pk_mul_f32 v[12:13], v[12:13], v[4:5]
	v_pk_mul_f32 v[14:15], v[14:15], v[6:7]
	v_pk_mul_f32 v[8:9], v[8:9], v[0:1]
	v_pk_mul_f32 v[10:11], v[10:11], v[2:3]
	v_pk_mul_f32 v[12:13], v[12:13], v[160:161]
	v_pk_mul_f32 v[14:15], v[14:15], v[162:163]
	v_pk_mul_f32 v[8:9], v[8:9], v[164:165]
	v_pk_mul_f32 v[10:11], v[10:11], v[166:167]
	v_cvt_pk_bf16_f32 v172, v12, v13
	v_cvt_pk_bf16_f32 v173, v14, v15
	v_cvt_pk_bf16_f32 v174, v8, v9
	v_cvt_pk_bf16_f32 v175, v10, v11
	v_add_u32_e32 v185, 0xf2000, v183
	global_store_dwordx4 v185, v[172:175], s[6:7]
	s_cbranch_vccz .LBB0_128
	s_waitcnt vmcnt(0)
	s_cmpk_gt_u32 s37, 0xff
	s_cbranch_scc1 .LBB0_135

.Lg893_mid:
	ds_read_b128 v[152:155], v151
	ds_read_b128 v[156:159], v151 offset:1024
	ds_read_b128 v[160:163], v151 offset:2048
	ds_read_b128 v[164:167], v151 offset:3072
	s_add_u32 s28, s28, 0x40000
	s_addc_u32 s29, s29, 0
	s_mov_b32 m0, s43
	ds_read_b128 v[168:171], v149 offset:32768
	ds_read_b128 v[172:175], v149 offset:33792
	ds_read_b128 v[176:179], v149 offset:34816
	ds_read_b128 v[180:183], v149 offset:35840
	ds_read_b128 v[184:187], v149 offset:36864
	ds_read_b128 v[188:191], v149 offset:37888
	ds_read_b128 v[192:195], v149 offset:38912
	ds_read_b128 v[196:199], v149 offset:39936
	global_load_lds_dwordx4 v134, s[28:29]
	s_mov_b32 m0, s44
	s_nop 0
	global_load_lds_dwordx4 v130, s[28:29]
	s_waitcnt lgkmcnt(8)
	s_barrier
	s_waitcnt lgkmcnt(0)
	s_waitcnt lgkmcnt(0)
	v_mfma_f32_16x16x32_bf16 v[124:127], v[152:155], v[168:171], v[124:127]
	v_mfma_f32_16x16x32_bf16 v[120:123], v[160:163], v[168:171], v[120:123]
	v_mfma_f32_16x16x32_bf16 v[108:111], v[152:155], v[176:179], v[108:111]
	v_mfma_f32_16x16x32_bf16 v[104:107], v[160:163], v[176:179], v[104:107]
	v_mfma_f32_16x16x32_bf16 v[92:95], v[152:155], v[184:187], v[92:95]
	v_mfma_f32_16x16x32_bf16 v[88:91], v[160:163], v[184:187], v[88:91]
	v_mfma_f32_16x16x32_bf16 v[76:79], v[152:155], v[192:195], v[76:79]
	v_mfma_f32_16x16x32_bf16 v[72:75], v[160:163], v[192:195], v[72:75]
	v_mfma_f32_16x16x32_bf16 v[124:127], v[156:159], v[172:175], v[124:127]
	v_mfma_f32_16x16x32_bf16 v[120:123], v[164:167], v[172:175], v[120:123]
	v_mfma_f32_16x16x32_bf16 v[108:111], v[156:159], v[180:183], v[108:111]
	v_mfma_f32_16x16x32_bf16 v[104:107], v[164:167], v[180:183], v[104:107]
	v_mfma_f32_16x16x32_bf16 v[92:95], v[156:159], v[188:191], v[92:95]
	v_mfma_f32_16x16x32_bf16 v[88:91], v[164:167], v[188:191], v[88:91]
	v_mfma_f32_16x16x32_bf16 v[76:79], v[156:159], v[196:199], v[76:79]
	v_mfma_f32_16x16x32_bf16 v[72:75], v[164:167], v[196:199], v[72:75]
	s_barrier
	s_add_i32 s28, 0, 0x1c000
	s_add_i32 s29, s58, s31
	v_add_u32_e32 v151, s28, v145
	s_mov_b32 m0, s29
	ds_read_b128 v[200:203], v151
	ds_read_b128 v[204:207], v151 offset:1024
	ds_read_b128 v[208:211], v151 offset:2048
	ds_read_b128 v[212:215], v151 offset:3072
	global_load_lds_dwordx4 v132, s[80:81]
	s_add_i32 m0, s29, 0x2000
	s_nop 0
	global_load_lds_dwordx4 v128, s[80:81]
	s_waitcnt vmcnt(10)
	s_barrier
	s_waitcnt lgkmcnt(0)
	s_waitcnt lgkmcnt(0)
	v_mfma_f32_16x16x32_bf16 v[116:119], v[200:203], v[168:171], v[116:119]
	v_mfma_f32_16x16x32_bf16 v[112:115], v[208:211], v[168:171], v[112:115]
	v_mfma_f32_16x16x32_bf16 v[100:103], v[200:203], v[176:179], v[100:103]
	v_mfma_f32_16x16x32_bf16 v[96:99], v[208:211], v[176:179], v[96:99]
	v_mfma_f32_16x16x32_bf16 v[84:87], v[200:203], v[184:187], v[84:87]
	v_mfma_f32_16x16x32_bf16 v[80:83], v[208:211], v[184:187], v[80:83]
	v_mfma_f32_16x16x32_bf16 v[68:71], v[200:203], v[192:195], v[68:71]
	v_mfma_f32_16x16x32_bf16 v[64:67], v[208:211], v[192:195], v[64:67]
	v_mfma_f32_16x16x32_bf16 v[116:119], v[204:207], v[172:175], v[116:119]
	v_mfma_f32_16x16x32_bf16 v[112:115], v[212:215], v[172:175], v[112:115]
	v_mfma_f32_16x16x32_bf16 v[100:103], v[204:207], v[180:183], v[100:103]
	v_mfma_f32_16x16x32_bf16 v[96:99], v[212:215], v[180:183], v[96:99]
	v_mfma_f32_16x16x32_bf16 v[84:87], v[204:207], v[188:191], v[84:87]
	v_mfma_f32_16x16x32_bf16 v[80:83], v[212:215], v[188:191], v[80:83]
	v_mfma_f32_16x16x32_bf16 v[68:71], v[204:207], v[196:199], v[68:71]
	v_mfma_f32_16x16x32_bf16 v[64:67], v[212:215], v[196:199], v[64:67]
	s_mov_b32 m0, s45
	s_barrier
	ds_read_b128 v[168:171], v149 offset:49152
	ds_read_b128 v[172:175], v149 offset:50176
	ds_read_b128 v[176:179], v149 offset:51200
	ds_read_b128 v[180:183], v149 offset:52224
	ds_read_b128 v[184:187], v149 offset:53248
	ds_read_b128 v[188:191], v149 offset:54272
	ds_read_b128 v[192:195], v149 offset:55296
	ds_read_b128 v[196:199], v149 offset:56320
	global_load_lds_dwordx4 v134, s[82:83]
	s_mov_b32 m0, s46
	s_nop 0
	global_load_lds_dwordx4 v130, s[82:83]
	s_barrier
	s_waitcnt lgkmcnt(0)
	s_waitcnt lgkmcnt(0)
	v_mfma_f32_16x16x32_bf16 v[60:63], v[152:155], v[168:171], v[60:63]
	v_mfma_f32_16x16x32_bf16 v[56:59], v[160:163], v[168:171], v[56:59]
	v_mfma_f32_16x16x32_bf16 v[44:47], v[152:155], v[176:179], v[44:47]
	v_mfma_f32_16x16x32_bf16 v[40:43], v[160:163], v[176:179], v[40:43]
	v_mfma_f32_16x16x32_bf16 v[28:31], v[152:155], v[184:187], v[28:31]
	v_mfma_f32_16x16x32_bf16 v[24:27], v[160:163], v[184:187], v[24:27]
	v_mfma_f32_16x16x32_bf16 v[12:15], v[152:155], v[192:195], v[12:15]
	v_mfma_f32_16x16x32_bf16 v[8:11], v[160:163], v[192:195], v[8:11]
	v_mfma_f32_16x16x32_bf16 v[60:63], v[156:159], v[172:175], v[60:63]
	v_mfma_f32_16x16x32_bf16 v[56:59], v[164:167], v[172:175], v[56:59]
	v_mfma_f32_16x16x32_bf16 v[44:47], v[156:159], v[180:183], v[44:47]
	v_mfma_f32_16x16x32_bf16 v[40:43], v[164:167], v[180:183], v[40:43]
	v_mfma_f32_16x16x32_bf16 v[28:31], v[156:159], v[188:191], v[28:31]
	v_mfma_f32_16x16x32_bf16 v[24:27], v[164:167], v[188:191], v[24:27]
	v_mfma_f32_16x16x32_bf16 v[12:15], v[156:159], v[196:199], v[12:15]
	v_mfma_f32_16x16x32_bf16 v[8:11], v[164:167], v[196:199], v[8:11]
	s_barrier
	s_add_u32 s26, s26, 0x40080
	s_addc_u32 s27, s27, 0
	s_add_i32 s28, s28, s31
	s_mov_b32 m0, s28
	s_nop 0
	global_load_lds_dwordx4 v132, s[26:27]
	s_add_i32 m0, s28, 0x2000
	s_nop 0
	global_load_lds_dwordx4 v128, s[26:27]
	s_waitcnt vmcnt(8)
	s_barrier
	v_mfma_f32_16x16x32_bf16 v[52:55], v[200:203], v[168:171], v[52:55]
	v_mfma_f32_16x16x32_bf16 v[48:51], v[208:211], v[168:171], v[48:51]
	v_mfma_f32_16x16x32_bf16 v[36:39], v[200:203], v[176:179], v[36:39]
	v_mfma_f32_16x16x32_bf16 v[32:35], v[208:211], v[176:179], v[32:35]
	v_mfma_f32_16x16x32_bf16 v[20:23], v[200:203], v[184:187], v[20:23]
	v_mfma_f32_16x16x32_bf16 v[16:19], v[208:211], v[184:187], v[16:19]
	v_mfma_f32_16x16x32_bf16 v[4:7], v[200:203], v[192:195], v[4:7]
	v_mfma_f32_16x16x32_bf16 v[0:3], v[208:211], v[192:195], v[0:3]
	v_mfma_f32_16x16x32_bf16 v[52:55], v[204:207], v[172:175], v[52:55]
	v_mfma_f32_16x16x32_bf16 v[48:51], v[212:215], v[172:175], v[48:51]
	v_mfma_f32_16x16x32_bf16 v[36:39], v[204:207], v[180:183], v[36:39]
	v_mfma_f32_16x16x32_bf16 v[32:35], v[212:215], v[180:183], v[32:35]
	v_mfma_f32_16x16x32_bf16 v[20:23], v[204:207], v[188:191], v[20:23]
	v_mfma_f32_16x16x32_bf16 v[16:19], v[212:215], v[188:191], v[16:19]
	v_mfma_f32_16x16x32_bf16 v[4:7], v[204:207], v[196:199], v[4:7]
	v_mfma_f32_16x16x32_bf16 v[0:3], v[212:215], v[196:199], v[0:3]
	s_add_i32 s57, s57, 2
	s_add_u32 s20, s20, 0x100
	s_addc_u32 s21, s21, 0
	s_add_u32 s55, s55, 0x100
	s_addc_u32 s56, s56, 0
	s_cmp_gt_u32 s57, 13
	s_barrier
	s_cbranch_scc0 .LBB0_893
	s_setprio 0
	v_lshl_add_u32 v180, s51, 10, v146
	ds_read2_b32 v[152:153], v180 offset1:16
	ds_read2_b32 v[154:155], v180 offset0:32 offset1:48
	ds_read2_b32 v[156:157], v180 offset0:128 offset1:144
	ds_read2_b32 v[158:159], v180 offset0:160 offset1:176
	v_lshl_or_b32 v181, s52, 7, v147
	v_lshl_add_u32 v182, s18, 8, v144
	s_and_b64 vcc, exec, s[4:5]
	s_mov_b32 s52, s10
	s_mov_b32 s18, s12
	s_mov_b64 s[26:27], s[16:17]
	s_mov_b32 s51, s50
	s_mov_b64 s[20:21], s[14:15]
	v_mul_u32_u24_e32 v183, s49, v182
	v_lshl_add_u32 v183, v181, 1, v183
	s_waitcnt lgkmcnt(0)
	v_mul_f32_e32 v176, 0xbfb8aa3b, v152
	v_mul_f32_e32 v177, v152, v152
	v_rcp_f32_e32 v178, v177
	v_pk_mul_f32 v[160:161], v[124:125], v[176:177] op_sel_hi:[1,0]
	v_pk_mul_f32 v[162:163], v[126:127], v[176:177] op_sel_hi:[1,0]
	v_pk_mul_f32 v[164:165], v[120:121], v[176:177] op_sel_hi:[1,0]
	v_pk_mul_f32 v[166:167], v[122:123], v[176:177] op_sel_hi:[1,0]
	v_exp_f32_e32 v160, v160
	v_exp_f32_e32 v161, v161
	v_exp_f32_e32 v162, v162
	v_exp_f32_e32 v163, v163
	v_exp_f32_e32 v164, v164
	v_exp_f32_e32 v165, v165
	v_exp_f32_e32 v166, v166
	v_exp_f32_e32 v167, v167
	v_pk_fma_f32 v[160:161], v[160:161], v[178:179], v[178:179] op_sel_hi:[1,0,0]
	v_pk_fma_f32 v[162:163], v[162:163], v[178:179], v[178:179] op_sel_hi:[1,0,0]
	v_pk_fma_f32 v[164:165], v[164:165], v[178:179], v[178:179] op_sel_hi:[1,0,0]
	v_pk_fma_f32 v[166:167], v[166:167], v[178:179], v[178:179] op_sel_hi:[1,0,0]
	v_rcp_f32_e32 v160, v160
	v_rcp_f32_e32 v161, v161
	v_rcp_f32_e32 v162, v162
	v_rcp_f32_e32 v163, v163
	v_rcp_f32_e32 v164, v164
	v_rcp_f32_e32 v165, v165
	v_rcp_f32_e32 v166, v166
	v_rcp_f32_e32 v167, v167
	v_pk_mul_f32 v[124:125], v[124:125], v[116:117]
	v_pk_mul_f32 v[126:127], v[126:127], v[118:119]
	v_pk_mul_f32 v[120:121], v[120:121], v[112:113]
	v_pk_mul_f32 v[122:123], v[122:123], v[114:115]
	v_pk_mul_f32 v[124:125], v[124:125], v[160:161]
	v_pk_mul_f32 v[126:127], v[126:127], v[162:163]
	v_pk_mul_f32 v[120:121], v[120:121], v[164:165]
	v_pk_mul_f32 v[122:123], v[122:123], v[166:167]
	v_cvt_pk_bf16_f32 v168, v124, v125
	v_cvt_pk_bf16_f32 v169, v126, v127
	v_cvt_pk_bf16_f32 v170, v120, v121
	v_cvt_pk_bf16_f32 v171, v122, v123
	global_store_dwordx4 v183, v[168:171], s[6:7]
	s_cmpk_gt_u32 s30, 0xff
	s_cbranch_scc1 .Lg893_nox
	s_barrier
	s_setprio 1
.Lg893_nox:
	v_mul_f32_e32 v176, 0xbfb8aa3b, v153
	v_mul_f32_e32 v177, v153, v153
	v_rcp_f32_e32 v178, v177
	v_pk_mul_f32 v[160:161], v[108:109], v[176:177] op_sel_hi:[1,0]
	v_pk_mul_f32 v[162:163], v[110:111], v[176:177] op_sel_hi:[1,0]
	v_pk_mul_f32 v[164:165], v[104:105], v[176:177] op_sel_hi:[1,0]
	v_pk_mul_f32 v[166:167], v[106:107], v[176:177] op_sel_hi:[1,0]
	v_exp_f32_e32 v160, v160
	v_exp_f32_e32 v161, v161
	v_exp_f32_e32 v162, v162
	v_exp_f32_e32 v163, v163
	v_exp_f32_e32 v164, v164
	v_exp_f32_e32 v165, v165
	v_exp_f32_e32 v166, v166
	v_exp_f32_e32 v167, v167
	v_pk_fma_f32 v[160:161], v[160:161], v[178:179], v[178:179] op_sel_hi:[1,0,0]
	v_pk_fma_f32 v[162:163], v[162:163], v[178:179], v[178:179] op_sel_hi:[1,0,0]
	v_pk_fma_f32 v[164:165], v[164:165], v[178:179], v[178:179] op_sel_hi:[1,0,0]
	v_pk_fma_f32 v[166:167], v[166:167], v[178:179], v[178:179] op_sel_hi:[1,0,0]
	v_rcp_f32_e32 v160, v160
	v_rcp_f32_e32 v161, v161
	v_rcp_f32_e32 v162, v162
	v_rcp_f32_e32 v163, v163
	v_rcp_f32_e32 v164, v164
	v_rcp_f32_e32 v165, v165
	v_rcp_f32_e32 v166, v166
	v_rcp_f32_e32 v167, v167
	v_pk_mul_f32 v[108:109], v[108:109], v[100:101]
	v_pk_mul_f32 v[110:111], v[110:111], v[102:103]
	v_pk_mul_f32 v[104:105], v[104:105], v[96:97]
	v_pk_mul_f32 v[106:107], v[106:107], v[98:99]
	v_pk_mul_f32 v[108:109], v[108:109], v[160:161]
	v_pk_mul_f32 v[110:111], v[110:111], v[162:163]
	v_pk_mul_f32 v[104:105], v[104:105], v[164:165]
	v_pk_mul_f32 v[106:107], v[106:107], v[166:167]
	v_cvt_pk_bf16_f32 v172, v108, v109
	v_cvt_pk_bf16_f32 v173, v110, v111
	v_cvt_pk_bf16_f32 v174, v104, v105
	v_cvt_pk_bf16_f32 v175, v106, v107
	v_add_u32_e32 v185, 0x16000, v183
	global_store_dwordx4 v185, v[172:175], s[6:7]
	v_mul_f32_e32 v176, 0xbfb8aa3b, v154
	v_mul_f32_e32 v177, v154, v154
	v_rcp_f32_e32 v178, v177
	v_pk_mul_f32 v[160:161], v[92:93], v[176:177] op_sel_hi:[1,0]
	v_pk_mul_f32 v[162:163], v[94:95], v[176:177] op_sel_hi:[1,0]
	v_pk_mul_f32 v[164:165], v[88:89], v[176:177] op_sel_hi:[1,0]
	v_pk_mul_f32 v[166:167], v[90:91], v[176:177] op_sel_hi:[1,0]
	v_exp_f32_e32 v160, v160
	v_exp_f32_e32 v161, v161
	v_exp_f32_e32 v162, v162
	v_exp_f32_e32 v163, v163
	v_exp_f32_e32 v164, v164
	v_exp_f32_e32 v165, v165
	v_exp_f32_e32 v166, v166
	v_exp_f32_e32 v167, v167
	v_pk_fma_f32 v[160:161], v[160:161], v[178:179], v[178:179] op_sel_hi:[1,0,0]
	v_pk_fma_f32 v[162:163], v[162:163], v[178:179], v[178:179] op_sel_hi:[1,0,0]
	v_pk_fma_f32 v[164:165], v[164:165], v[178:179], v[178:179] op_sel_hi:[1,0,0]
	v_pk_fma_f32 v[166:167], v[166:167], v[178:179], v[178:179] op_sel_hi:[1,0,0]
	v_rcp_f32_e32 v160, v160
	v_rcp_f32_e32 v161, v161
	v_rcp_f32_e32 v162, v162
	v_rcp_f32_e32 v163, v163
	v_rcp_f32_e32 v164, v164
	v_rcp_f32_e32 v165, v165
	v_rcp_f32_e32 v166, v166
	v_rcp_f32_e32 v167, v167
	v_pk_mul_f32 v[92:93], v[92:93], v[84:85]
	v_pk_mul_f32 v[94:95], v[94:95], v[86:87]
	v_pk_mul_f32 v[88:89], v[88:89], v[80:81]
	v_pk_mul_f32 v[90:91], v[90:91], v[82:83]
	v_pk_mul_f32 v[92:93], v[92:93], v[160:161]
	v_pk_mul_f32 v[94:95], v[94:95], v[162:163]
	v_pk_mul_f32 v[88:89], v[88:89], v[164:165]
	v_pk_mul_f32 v[90:91], v[90:91], v[166:167]
	v_cvt_pk_bf16_f32 v168, v92, v93
	v_cvt_pk_bf16_f32 v169, v94, v95
	v_cvt_pk_bf16_f32 v170, v88, v89
	v_cvt_pk_bf16_f32 v171, v90, v91
	v_add_u32_e32 v184, 0x2c000, v183
	global_store_dwordx4 v184, v[168:171], s[6:7]
	v_mul_f32_e32 v176, 0xbfb8aa3b, v155
	v_mul_f32_e32 v177, v155, v155
	v_rcp_f32_e32 v178, v177
	v_pk_mul_f32 v[160:161], v[76:77], v[176:177] op_sel_hi:[1,0]
	v_pk_mul_f32 v[162:163], v[78:79], v[176:177] op_sel_hi:[1,0]
	v_pk_mul_f32 v[164:165], v[72:73], v[176:177] op_sel_hi:[1,0]
	v_pk_mul_f32 v[166:167], v[74:75], v[176:177] op_sel_hi:[1,0]
	v_exp_f32_e32 v160, v160
	v_exp_f32_e32 v161, v161
	v_exp_f32_e32 v162, v162
	v_exp_f32_e32 v163, v163
	v_exp_f32_e32 v164, v164
	v_exp_f32_e32 v165, v165
	v_exp_f32_e32 v166, v166
	v_exp_f32_e32 v167, v167
	v_pk_fma_f32 v[160:161], v[160:161], v[178:179], v[178:179] op_sel_hi:[1,0,0]
	v_pk_fma_f32 v[162:163], v[162:163], v[178:179], v[178:179] op_sel_hi:[1,0,0]
	v_pk_fma_f32 v[164:165], v[164:165], v[178:179], v[178:179] op_sel_hi:[1,0,0]
	v_pk_fma_f32 v[166:167], v[166:167], v[178:179], v[178:179] op_sel_hi:[1,0,0]
	v_rcp_f32_e32 v160, v160
	v_rcp_f32_e32 v161, v161
	v_rcp_f32_e32 v162, v162
	v_rcp_f32_e32 v163, v163
	v_rcp_f32_e32 v164, v164
	v_rcp_f32_e32 v165, v165
	v_rcp_f32_e32 v166, v166
	v_rcp_f32_e32 v167, v167
	v_pk_mul_f32 v[76:77], v[76:77], v[68:69]
	v_pk_mul_f32 v[78:79], v[78:79], v[70:71]
	v_pk_mul_f32 v[72:73], v[72:73], v[64:65]
	v_pk_mul_f32 v[74:75], v[74:75], v[66:67]
	v_pk_mul_f32 v[76:77], v[76:77], v[160:161]
	v_pk_mul_f32 v[78:79], v[78:79], v[162:163]
	v_pk_mul_f32 v[72:73], v[72:73], v[164:165]
	v_pk_mul_f32 v[74:75], v[74:75], v[166:167]
	v_cvt_pk_bf16_f32 v172, v76, v77
	v_cvt_pk_bf16_f32 v173, v78, v79
	v_cvt_pk_bf16_f32 v174, v72, v73
	v_cvt_pk_bf16_f32 v175, v74, v75
	v_add_u32_e32 v185, 0x42000, v183
	global_store_dwordx4 v185, v[172:175], s[6:7]
	v_mul_f32_e32 v176, 0xbfb8aa3b, v156
	v_mul_f32_e32 v177, v156, v156
	v_rcp_f32_e32 v178, v177
	v_pk_mul_f32 v[160:161], v[60:61], v[176:177] op_sel_hi:[1,0]
	v_pk_mul_f32 v[162:163], v[62:63], v[176:177] op_sel_hi:[1,0]
	v_pk_mul_f32 v[164:165], v[56:57], v[176:177] op_sel_hi:[1,0]
	v_pk_mul_f32 v[166:167], v[58:59], v[176:177] op_sel_hi:[1,0]
	v_exp_f32_e32 v160, v160
	v_exp_f32_e32 v161, v161
	v_exp_f32_e32 v162, v162
	v_exp_f32_e32 v163, v163
	v_exp_f32_e32 v164, v164
	v_exp_f32_e32 v165, v165
	v_exp_f32_e32 v166, v166
	v_exp_f32_e32 v167, v167
	v_pk_fma_f32 v[160:161], v[160:161], v[178:179], v[178:179] op_sel_hi:[1,0,0]
	v_pk_fma_f32 v[162:163], v[162:163], v[178:179], v[178:179] op_sel_hi:[1,0,0]
	v_pk_fma_f32 v[164:165], v[164:165], v[178:179], v[178:179] op_sel_hi:[1,0,0]
	v_pk_fma_f32 v[166:167], v[166:167], v[178:179], v[178:179] op_sel_hi:[1,0,0]
	v_rcp_f32_e32 v160, v160
	v_rcp_f32_e32 v161, v161
	v_rcp_f32_e32 v162, v162
	v_rcp_f32_e32 v163, v163
	v_rcp_f32_e32 v164, v164
	v_rcp_f32_e32 v165, v165
	v_rcp_f32_e32 v166, v166
	v_rcp_f32_e32 v167, v167
	v_pk_mul_f32 v[60:61], v[60:61], v[52:53]
	v_pk_mul_f32 v[62:63], v[62:63], v[54:55]
	v_pk_mul_f32 v[56:57], v[56:57], v[48:49]
	v_pk_mul_f32 v[58:59], v[58:59], v[50:51]
	v_pk_mul_f32 v[60:61], v[60:61], v[160:161]
	v_pk_mul_f32 v[62:63], v[62:63], v[162:163]
	v_pk_mul_f32 v[56:57], v[56:57], v[164:165]
	v_pk_mul_f32 v[58:59], v[58:59], v[166:167]
	v_cvt_pk_bf16_f32 v168, v60, v61
	v_cvt_pk_bf16_f32 v169, v62, v63
	v_cvt_pk_bf16_f32 v170, v56, v57
	v_cvt_pk_bf16_f32 v171, v58, v59
	v_add_u32_e32 v184, 0xb0000, v183
	global_store_dwordx4 v184, v[168:171], s[6:7]
	v_mul_f32_e32 v176, 0xbfb8aa3b, v157
	v_mul_f32_e32 v177, v157, v157
	v_rcp_f32_e32 v178, v177
	v_pk_mul_f32 v[160:161], v[44:45], v[176:177] op_sel_hi:[1,0]
	v_pk_mul_f32 v[162:163], v[46:47], v[176:177] op_sel_hi:[1,0]
	v_pk_mul_f32 v[164:165], v[40:41], v[176:177] op_sel_hi:[1,0]
	v_pk_mul_f32 v[166:167], v[42:43], v[176:177] op_sel_hi:[1,0]
	v_exp_f32_e32 v160, v160
	v_exp_f32_e32 v161, v161
	v_exp_f32_e32 v162, v162
	v_exp_f32_e32 v163, v163
	v_exp_f32_e32 v164, v164
	v_exp_f32_e32 v165, v165
	v_exp_f32_e32 v166, v166
	v_exp_f32_e32 v167, v167
	v_pk_fma_f32 v[160:161], v[160:161], v[178:179], v[178:179] op_sel_hi:[1,0,0]
	v_pk_fma_f32 v[162:163], v[162:163], v[178:179], v[178:179] op_sel_hi:[1,0,0]
	v_pk_fma_f32 v[164:165], v[164:165], v[178:179], v[178:179] op_sel_hi:[1,0,0]
	v_pk_fma_f32 v[166:167], v[166:167], v[178:179], v[178:179] op_sel_hi:[1,0,0]
	v_rcp_f32_e32 v160, v160
	v_rcp_f32_e32 v161, v161
	v_rcp_f32_e32 v162, v162
	v_rcp_f32_e32 v163, v163
	v_rcp_f32_e32 v164, v164
	v_rcp_f32_e32 v165, v165
	v_rcp_f32_e32 v166, v166
	v_rcp_f32_e32 v167, v167
	v_pk_mul_f32 v[44:45], v[44:45], v[36:37]
	v_pk_mul_f32 v[46:47], v[46:47], v[38:39]
	v_pk_mul_f32 v[40:41], v[40:41], v[32:33]
	v_pk_mul_f32 v[42:43], v[42:43], v[34:35]
	v_pk_mul_f32 v[44:45], v[44:45], v[160:161]
	v_pk_mul_f32 v[46:47], v[46:47], v[162:163]
	v_pk_mul_f32 v[40:41], v[40:41], v[164:165]
	v_pk_mul_f32 v[42:43], v[42:43], v[166:167]
	v_cvt_pk_bf16_f32 v172, v44, v45
	v_cvt_pk_bf16_f32 v173, v46, v47
	v_cvt_pk_bf16_f32 v174, v40, v41
	v_cvt_pk_bf16_f32 v175, v42, v43
	v_add_u32_e32 v185, 0xc6000, v183
	global_store_dwordx4 v185, v[172:175], s[6:7]
	v_mul_f32_e32 v176, 0xbfb8aa3b, v158
	v_mul_f32_e32 v177, v158, v158
	v_rcp_f32_e32 v178, v177
	v_pk_mul_f32 v[160:161], v[28:29], v[176:177] op_sel_hi:[1,0]
	v_pk_mul_f32 v[162:163], v[30:31], v[176:177] op_sel_hi:[1,0]
	v_pk_mul_f32 v[164:165], v[24:25], v[176:177] op_sel_hi:[1,0]
	v_pk_mul_f32 v[166:167], v[26:27], v[176:177] op_sel_hi:[1,0]
	v_exp_f32_e32 v160, v160
	v_exp_f32_e32 v161, v161
	v_exp_f32_e32 v162, v162
	v_exp_f32_e32 v163, v163
	v_exp_f32_e32 v164, v164
	v_exp_f32_e32 v165, v165
	v_exp_f32_e32 v166, v166
	v_exp_f32_e32 v167, v167
	v_pk_fma_f32 v[160:161], v[160:161], v[178:179], v[178:179] op_sel_hi:[1,0,0]
	v_pk_fma_f32 v[162:163], v[162:163], v[178:179], v[178:179] op_sel_hi:[1,0,0]
	v_pk_fma_f32 v[164:165], v[164:165], v[178:179], v[178:179] op_sel_hi:[1,0,0]
	v_pk_fma_f32 v[166:167], v[166:167], v[178:179], v[178:179] op_sel_hi:[1,0,0]
	v_rcp_f32_e32 v160, v160
	v_rcp_f32_e32 v161, v161
	v_rcp_f32_e32 v162, v162
	v_rcp_f32_e32 v163, v163
	v_rcp_f32_e32 v164, v164
	v_rcp_f32_e32 v165, v165
	v_rcp_f32_e32 v166, v166
	v_rcp_f32_e32 v167, v167
	v_pk_mul_f32 v[28:29], v[28:29], v[20:21]
	v_pk_mul_f32 v[30:31], v[30:31], v[22:23]
	v_pk_mul_f32 v[24:25], v[24:25], v[16:17]
	v_pk_mul_f32 v[26:27], v[26:27], v[18:19]
	v_pk_mul_f32 v[28:29], v[28:29], v[160:161]
	v_pk_mul_f32 v[30:31], v[30:31], v[162:163]
	v_pk_mul_f32 v[24:25], v[24:25], v[164:165]
	v_pk_mul_f32 v[26:27], v[26:27], v[166:167]
	v_cvt_pk_bf16_f32 v168, v28, v29
	v_cvt_pk_bf16_f32 v169, v30, v31
	v_cvt_pk_bf16_f32 v170, v24, v25
	v_cvt_pk_bf16_f32 v171, v26, v27
	v_add_u32_e32 v184, 0xdc000, v183
	global_store_dwordx4 v184, v[168:171], s[6:7]
	v_mul_f32_e32 v176, 0xbfb8aa3b, v159
	v_mul_f32_e32 v177, v159, v159
	v_rcp_f32_e32 v178, v177
	v_pk_mul_f32 v[160:161], v[12:13], v[176:177] op_sel_hi:[1,0]
	v_pk_mul_f32 v[162:163], v[14:15], v[176:177] op_sel_hi:[1,0]
	v_pk_mul_f32 v[164:165], v[8:9], v[176:177] op_sel_hi:[1,0]
	v_pk_mul_f32 v[166:167], v[10:11], v[176:177] op_sel_hi:[1,0]
	v_exp_f32_e32 v160, v160
	v_exp_f32_e32 v161, v161
	v_exp_f32_e32 v162, v162
	v_exp_f32_e32 v163, v163
	v_exp_f32_e32 v164, v164
	v_exp_f32_e32 v165, v165
	v_exp_f32_e32 v166, v166
	v_exp_f32_e32 v167, v167
	v_pk_fma_f32 v[160:161], v[160:161], v[178:179], v[178:179] op_sel_hi:[1,0,0]
	v_pk_fma_f32 v[162:163], v[162:163], v[178:179], v[178:179] op_sel_hi:[1,0,0]
	v_pk_fma_f32 v[164:165], v[164:165], v[178:179], v[178:179] op_sel_hi:[1,0,0]
	v_pk_fma_f32 v[166:167], v[166:167], v[178:179], v[178:179] op_sel_hi:[1,0,0]
	v_rcp_f32_e32 v160, v160
	v_rcp_f32_e32 v161, v161
	v_rcp_f32_e32 v162, v162
	v_rcp_f32_e32 v163, v163
	v_rcp_f32_e32 v164, v164
	v_rcp_f32_e32 v165, v165
	v_rcp_f32_e32 v166, v166
	v_rcp_f32_e32 v167, v167
	v_pk_mul_f32 v[12:13], v[12:13], v[4:5]
	v_pk_mul_f32 v[14:15], v[14:15], v[6:7]
	v_pk_mul_f32 v[8:9], v[8:9], v[0:1]
	v_pk_mul_f32 v[10:11], v[10:11], v[2:3]
	v_pk_mul_f32 v[12:13], v[12:13], v[160:161]
	v_pk_mul_f32 v[14:15], v[14:15], v[162:163]
	v_pk_mul_f32 v[8:9], v[8:9], v[164:165]
	v_pk_mul_f32 v[10:11], v[10:11], v[166:167]
	v_cvt_pk_bf16_f32 v172, v12, v13
	v_cvt_pk_bf16_f32 v173, v14, v15
	v_cvt_pk_bf16_f32 v174, v8, v9
	v_cvt_pk_bf16_f32 v175, v10, v11
	v_add_u32_e32 v185, 0xf2000, v183
	global_store_dwordx4 v185, v[172:175], s[6:7]
	s_cbranch_vccz .LBB0_890
	s_waitcnt vmcnt(0)
	s_cmpk_gt_u32 s30, 0xff
	s_cbranch_scc1 .LBB0_897
